# MLA loop priority: static raise of the trailing half replaced by symmetric per-segment levels (s_setprio 2 around each wave's QK and P.V MFMA runs, 0 during softmax)
# speedup vs baseline: 1.0119x; 1.0043x over previous
; DEV int ltid() { int t = threadIdx.x; asm volatile("" : "+v"(t)); return t; }
; DEV int v_st(int k, int c) { const int kk = (k & ~0xC) | ((k & 4) << 1) | ((k & 8) >> 1); return ((kk >> 3) * 4 + (c >> 5)) * 512 + ((kk & 7) * 32 + (c & 31)) * 2; }
; DEV int v_rd_base(int lane) { return ((lane & 3) << 3) | (((lane >> 2) & 3) << 6) | (((lane >> 4) & 1) << 5) | (((lane >> 5) & 1) << 8); }
; #define SWRITE(b) do { *(bf16x8*)(V_lds + (b) * SHM_V + vst0) = svs0; *(bf16x8*)(V_lds + (b) * SHM_V + vst1) = svs1; \
;     _Pragma("unroll") for (int i_ = 0; i_ < NKP; ++i_) *(bf16x8*)(K_lds + (b) * KT + klds[i_]) = sks[i_]; } while (0)
; template <int DQK, bool WIN, bool TWO>
; DEV void attn_unit(const bf16_t* Qb, int ldq, const bf16_t* __restrict__ Kh, int ldk, const bf16_t* __restrict__ Vh, int ldv,
;                    bf16_t* Ob, int ldo, int kbeg, int NT, int q0, float sink, const float SCALE, char* lds) {
;     ...
;   const int tid = ltid(), wid = tid >> 6, lane = tid & 63, r32 = lane & 31, hi = lane >> 5;
;   char* V_lds = lds; char* K_lds = lds + 2 * SHM_V;
;   float* wsf = (float*)(lds + 2 * SHM_V + 2 * KT) + wid * 64; float* li_l = wsf; float* al_l = wsf + 32;
;   float m_reg = -1e30f, l_reg = 0;
;   f32x16 o[4];
; #pragma unroll
;   for (int d = 0; d < 4; ++d)
; #pragma unroll
;     for (int r = 0; r < 16; ++r) o[d][r] = 0.f;
;   constexpr int NQR = TWO ? 4 : DQK / 16;
;   bf16x8 qr[NQR];
;   const bf16_t* Qw = Qb + (size_t)(wid * 32 + r32) * ldq + hi * 8;
;   char* qlds = lds + 2 * SHM_V + 2 * KT + 2048 + wid * 8192 + lane * 16;
; #pragma unroll
;   for (int d0 = 0; d0 < NQR; ++d0) qr[d0] = *(const bf16x8*)(Qw + d0 * 16);
; #pragma unroll
;   for (int d0 = NQR; d0 < DQK / 16; ++d0) *(bf16x8*)(qlds + (d0 - NQR) * 1024) = *(const bf16x8*)(Qw + d0 * 16);
;   const int sr = tid >> 4, sc = (tid & 15) * 8, vst0 = v_st(sr, sc), vst1 = v_st(32 + sr, sc);
;   const int vb0 = (int)(uintptr_t)V_lds + v_rd_base(lane);
;   const unsigned voff = (unsigned)(sr * ldv + sc) * 2u, vstep = (unsigned)ldv * 64u;
;   unsigned koff[NKP]; int klds[NKP];
; #pragma unroll
;   for (int i = 0; i < NKP; ++i) { const int p = tid + i * NTHR; const int kr = p / PPR, kc = (p % PPR) * 8; koff[i] = (unsigned)(kr * ldk + kc) * 2u; klds[i] = kr * KROW + kc * 2; }
;   const int qpos = q0 + wid * 32 + r32;
;   bf16x8 svs0, svs1, sks[NKP];
;     ...
;   SLOAD(kbeg); SWAIT(); SWRITE(0); __syncthreads();
.LBB0_460:
	s_and_b32 s0, s21, 7
	s_bfe_u32 s1, s26, 0x50003
	v_readlane_b32 s2, v252, 46
	s_mul_i32 s35, s0, 0x180
	s_lshl_b32 s34, s0, 8
	s_ashr_i32 s0, s26, 8
	s_and_b32 s18, s1, s2
	v_readlane_b32 s2, v253, 50
	s_lshr_b32 s1, s1, s51
	s_lshl_b32 s0, s0, s2
	s_add_i32 s0, s1, s0
	s_ashr_i32 s1, s0, 31
	v_readlane_b32 s2, v249, 0
	s_and_b32 s24, s26, 7
	s_lshl_b64 s[2:3], s[0:1], s2
	s_lshl_b32 s0, s18, 8
	s_add_u32 s0, s2, s0
	s_addc_u32 s1, s3, 0
	s_mul_i32 s18, s1, 0xc00
	s_mul_hi_u32 s19, s0, 0xc00
	s_add_i32 s19, s19, s18
	s_mul_i32 s18, s0, 0xc00
	s_add_u32 s18, s78, s18
	s_addc_u32 s19, s79, s19
	s_mul_i32 s25, s24, 0x180
	s_add_u32 s38, s18, s25
	s_mul_i32 s18, s3, 0xc00
	s_mul_hi_u32 s40, s2, 0xc00
	s_addc_u32 s39, s19, 0
	s_add_i32 s40, s40, s18
	s_mul_i32 s41, s2, 0xc00
	v_readlane_b32 s4, v250, 0
	v_readlane_b32 s5, v250, 1
	s_add_u32 s18, s4, s41
	s_addc_u32 s19, s5, s40
	s_add_u32 s18, s18, s25
	s_addc_u32 s19, s19, 0
	s_lshl_b64 s[2:3], s[2:3], 11
	v_readlane_b32 s4, v249, 6
	v_readlane_b32 s5, v249, 7
	s_add_u32 s25, s4, s2
	s_addc_u32 s42, s5, s3
	s_lshl_b32 s27, s24, 7
	s_lshl_b32 s24, s24, 8
	v_mov_b32_e32 v2, v204
	s_add_u32 s24, s25, s24
	s_addc_u32 s25, s42, 0
	v_ashrrev_i32_e32 v3, 6, v2
	v_and_b32_e32 v175, 31, v2
	v_and_b32_e32 v0, 0x3fffffc0, v2
	s_add_i32 s42, 0, 0x14800
	v_lshlrev_b32_e32 v174, 5, v3
	v_lshl_add_u32 v173, v0, 2, s42
	v_bfe_u32 v172, v2, 5, 1
	v_or_b32_e32 v4, v174, v175
	v_mov_b64_e32 v[0:1], s[38:39]
	s_movk_i32 s4, 0xc00
	v_mad_i64_i32 v[0:1], s[38:39], v4, s4, v[0:1]
	v_lshlrev_b32_e32 v196, 4, v172
	v_lshl_add_u64 v[0:1], v[0:1], 0, v[196:197]
	global_load_dwordx4 v[140:143], v[0:1], off
	global_load_dwordx4 v[136:139], v[0:1], off offset:32
	global_load_dwordx4 v[132:135], v[0:1], off offset:64
	global_load_dwordx4 v[128:131], v[0:1], off offset:96
	global_load_dwordx4 v[124:127], v[0:1], off offset:128
	global_load_dwordx4 v[120:123], v[0:1], off offset:160
	global_load_dwordx4 v[116:119], v[0:1], off offset:192
	global_load_dwordx4 v[112:115], v[0:1], off offset:224
	global_load_dwordx4 v[108:111], v[0:1], off offset:256
	global_load_dwordx4 v[104:107], v[0:1], off offset:288
	global_load_dwordx4 v[100:103], v[0:1], off offset:320
	global_load_dwordx4 v[96:99], v[0:1], off offset:352
	v_ashrrev_i32_e32 v0, 4, v2
	v_lshlrev_b32_e32 v31, 13, v3
	v_and_b32_e32 v3, 0xfffff0, v0
	v_lshlrev_b32_e32 v4, 1, v0
	v_and_or_b32 v3, v4, 8, v3
	v_lshrrev_b32_e32 v4, 1, v0
	v_and_b32_e32 v6, 3, v0
	v_and_or_b32 v4, v4, 4, v6
	v_lshlrev_b32_e32 v38, 6, v4
	v_add_u32_e32 v4, 32, v0
	v_and_b32_e32 v6, 0xfffff0, v4
	v_lshlrev_b32_e32 v4, 1, v4
	v_lshlrev_b32_e32 v33, 3, v2
	v_and_or_b32 v4, v4, 8, v6
	v_bfe_u32 v5, v33, 5, 2
	v_lshrrev_b32_e32 v4, 1, v4
	v_or_b32_e32 v4, v4, v5
	s_mov_b32 s5, 0x2aaaaaab
	v_lshrrev_b32_e32 v3, 1, v3
	v_lshlrev_b32_e32 v39, 9, v4
	v_mul_hi_i32 v4, v2, s5
	v_or_b32_e32 v3, v3, v5
	v_lshrrev_b32_e32 v5, 31, v4
	v_ashrrev_i32_e32 v4, 2, v4
	v_add_u32_e32 v4, v4, v5
	v_mul_lo_u32 v5, v4, 24
	v_sub_u32_e32 v5, v2, v5
	v_mul_lo_u32 v6, v4, s4
	v_lshl_add_u32 v16, v5, 4, v6
	s_movk_i32 s39, 0xf590
	v_mad_u64_u32 v[20:21], s[42:43], v4, s39, v[16:17]
	v_add_u32_e32 v4, 0x200, v2
	v_mul_hi_i32 v5, v4, s5
	v_lshrrev_b32_e32 v6, 31, v5
	v_ashrrev_i32_e32 v5, 2, v5
	v_add_u32_e32 v5, v5, v6
	v_mul_lo_u32 v6, v5, 24
	v_and_b32_e32 v30, 63, v2
	v_lshlrev_b32_e32 v40, 1, v2
	v_sub_u32_e32 v4, v4, v6
	v_mul_lo_u32 v6, v5, s4
	v_add_u32_e32 v2, 0x400, v2
	s_waitcnt lgkmcnt(0)
	v_lshl_add_u32 v18, v4, 4, v6
	v_mul_hi_i32 v4, v2, s5
	v_mad_u64_u32 v[24:25], s[42:43], v5, s39, v[18:19]
	v_lshrrev_b32_e32 v5, 31, v4
	v_ashrrev_i32_e32 v4, 2, v4
	v_and_b32_e32 v1, 0x78, v33
	v_add_u32_e32 v4, v4, v5
	v_lshlrev_b32_e32 v1, 1, v1
	v_mul_lo_u32 v5, v4, 24
	v_lshlrev_b32_e32 v3, 9, v3
	v_sub_u32_e32 v2, v2, v5
	v_mul_lo_u32 v5, v4, s4
	v_and_b32_e32 v21, 48, v1
	v_lshl_or_b32 v28, v0, 11, v1
	v_lshl_add_u32 v22, v2, 4, v5
	v_or3_b32 v25, v3, v38, v21
	global_load_dwordx4 v[0:3], v28, s[24:25]
	global_load_dwordx4 v[34:37], v22, s[18:19]
	v_mov_b32_e32 v29, v197
	v_mad_u64_u32 v[26:27], s[42:43], v4, s39, v[22:23]
	v_lshl_add_u64 v[4:5], s[24:25], 0, v[28:29]
	s_mov_b32 s4, 0x10000
	v_add_co_u32_e32 v4, vcc, s4, v4
	global_load_dwordx4 v[8:11], v16, s[18:19]
	global_load_dwordx4 v[12:15], v18, s[18:19]
	v_addc_co_u32_e32 v5, vcc, 0, v5, vcc
	global_load_dwordx4 v[4:7], v[4:5], off
	v_add_u32_e32 v179, 0, v25
	s_add_i32 s38, 0, 0x15000
	s_waitcnt vmcnt(0)
	s_movk_i32 s18, 0x118
	v_lshlrev_b32_e32 v32, 4, v30
	s_cmp_lg_u32 0, -1
	v_and_b32_e32 v27, 0xc0, v32
	v_or3_b32 v21, v39, v38, v21
	v_add_u32_e32 v180, 0, v21
	v_add_u32_e32 v182, 0, v20
	v_add_u32_e32 v183, 0, v24
	v_mov_b32_e32 v17, v197
	v_mov_b32_e32 v19, v197
	v_mov_b32_e32 v23, v197
	v_add_u32_e32 v184, 0, v26
	v_add3_u32 v181, s38, v31, v32
	v_cmp_gt_u32_e64 s[38:39], 32, v30
	s_mov_b32 s24, 0
	s_mov_b32 s101, 0
	v_lshl_add_u32 v176, v175, 2, v173
	v_mov_b32_e32 v187, 0
	v_mov_b32_e32 v178, 0
	v_mov_b32_e32 v226, 0
	v_mov_b32_e32 v227, 0
	v_mov_b32_e32 v228, 0
	v_mov_b32_e32 v229, 0
	v_mov_b32_e32 v230, 0
	v_mov_b32_e32 v231, 0
	v_mov_b32_e32 v232, 0
	v_mov_b32_e32 v233, 0
	v_mov_b32_e32 v234, 0
	v_mov_b32_e32 v235, 0
	v_mov_b32_e32 v236, 0
	v_mov_b32_e32 v237, 0
	v_mov_b32_e32 v238, 0
	v_mov_b32_e32 v239, 0
	v_mov_b32_e32 v240, 0
	v_mov_b32_e32 v241, 0
	s_waitcnt vmcnt(0)
; DEV int v_st(int k, int c) { const int kk = (k & ~0xC) | ((k & 4) << 1) | ((k & 8) >> 1); return ((kk >> 3) * 4 + (c >> 5)) * 512 + ((kk & 7) * 32 + (c & 31)) * 2; }
; DEV int v_rd_base(int lane) { return ((lane & 3) << 3) | (((lane >> 2) & 3) << 6) | (((lane >> 4) & 1) << 5) | (((lane >> 5) & 1) << 8); }
; #define SLOAD(k0) do { const char* Vt_ = (const char*)(Vh + (size_t)(k0) * ldv); const char* Kt_ = (const char*)(Kh + (size_t)(k0) * ldk); \
;     svs0 = *(const bf16x8*)(Vt_ + voff); svs1 = *(const bf16x8*)(Vt_ + vstep + voff); \
;     _Pragma("unroll") for (int i_ = 0; i_ < NKP; ++i_) sks[i_] = *(const bf16x8*)(Kt_ + koff[i_]); } while (0)
; #define SWRITE(b) do { *(bf16x8*)(V_lds + (b) * SHM_V + vst0) = svs0; *(bf16x8*)(V_lds + (b) * SHM_V + vst1) = svs1; \
;     _Pragma("unroll") for (int i_ = 0; i_ < NKP; ++i_) *(bf16x8*)(K_lds + (b) * KT + klds[i_]) = sks[i_]; } while (0)
; template <int DQK, bool WIN, bool TWO>
; DEV void attn_unit(const bf16_t* Qb, int ldq, const bf16_t* __restrict__ Kh, int ldk, const bf16_t* __restrict__ Vh, int ldv,
;                    bf16_t* Ob, int ldo, int kbeg, int NT, int q0, float sink, const float SCALE, char* lds) {
;     ...
;   float m_reg = -1e30f, l_reg = 0;
;   f32x16 o[4];
; #pragma unroll
;   for (int d = 0; d < 4; ++d)
; #pragma unroll
;     for (int r = 0; r < 16; ++r) o[d][r] = 0.f;
;   constexpr int NQR = TWO ? 4 : DQK / 16;
;   bf16x8 qr[NQR];
;   const bf16_t* Qw = Qb + (size_t)(wid * 32 + r32) * ldq + hi * 8;
;   char* qlds = lds + 2 * SHM_V + 2 * KT + 2048 + wid * 8192 + lane * 16;
; #pragma unroll
;   for (int d0 = 0; d0 < NQR; ++d0) qr[d0] = *(const bf16x8*)(Qw + d0 * 16);
; #pragma unroll
;   for (int d0 = NQR; d0 < DQK / 16; ++d0) *(bf16x8*)(qlds + (d0 - NQR) * 1024) = *(const bf16x8*)(Qw + d0 * 16);
;   const int sr = tid >> 4, sc = (tid & 15) * 8, vst0 = v_st(sr, sc), vst1 = v_st(32 + sr, sc);
;   const int vb0 = (int)(uintptr_t)V_lds + v_rd_base(lane);
;   const unsigned voff = (unsigned)(sr * ldv + sc) * 2u, vstep = (unsigned)ldv * 64u;
;   unsigned koff[NKP]; int klds[NKP];
; #pragma unroll
;   for (int i = 0; i < NKP; ++i) { const int p = tid + i * NTHR; const int kr = p / PPR, kc = (p % PPR) * 8; koff[i] = (unsigned)(kr * ldk + kc) * 2u; klds[i] = kr * KROW + kc * 2; }
;   const int qpos = q0 + wid * 32 + r32;
;   bf16x8 svs0, svs1, sks[NKP];
;     ...
;   SLOAD(kbeg); SWAIT(); SWRITE(0); __syncthreads();
	ds_write_b128 v179, v[0:3]
	v_and_b32_e32 v0, 32, v40
	v_and_or_b32 v0, v33, s18, v0
	s_movk_i32 s18, 0x190
	v_mad_u32_u24 v185, v175, s18, 0
	s_cselect_b32 s18, 0, 0
	v_add3_u32 v177, v27, s18, v0
	s_add_u32 s18, s41, s35
	s_addc_u32 s19, s40, 0
	s_add_u32 s18, s18, 0x2c934000
	s_addc_u32 s19, s19, 0
	s_or_b32 s2, s2, s34
	v_lshl_add_u64 v[164:165], s[18:19], 0, v[16:17]
	ds_write_b128 v180, v[4:7]
	ds_write_b128 v182, v[8:11] offset:32768
	ds_write_b128 v183, v[12:15] offset:32768
	v_mov_b32_e32 v14, v197
	v_mov_b32_e32 v15, v197
	ds_write_b128 v184, v[34:37] offset:32768
	v_lshl_add_u64 v[166:167], s[18:19], 0, v[18:19]
	v_lshl_add_u64 v[168:169], s[18:19], 0, v[22:23]
	v_lshl_add_u64 v[170:171], s[2:3], 0, v[28:29]
	v_lshl_add_u64 v[164:165], s[64:65], 0, v[164:165]
	v_lshl_add_u64 v[166:167], s[64:65], 0, v[166:167]
	v_lshl_add_u64 v[168:169], s[64:65], 0, v[168:169]
	v_lshl_add_u64 v[170:171], s[64:65], 0, v[170:171]
	s_mov_b64 s[2:3], 0x32924000
	v_lshl_add_u64 v[246:247], s[2:3], 0, v[170:171]
	s_mov_b64 s[2:3], 0x32934000
	v_lshl_add_u64 v[170:171], s[2:3], 0, v[170:171]
	v_mov_b32_e32 v0, v197
	v_mov_b32_e32 v1, v197
	v_mov_b32_e32 v2, v197
	v_mov_b32_e32 v3, v197
	v_mov_b32_e32 v4, v197
	v_mov_b32_e32 v5, v197
	v_mov_b32_e32 v6, v197
	v_mov_b32_e32 v7, v197
	v_mov_b32_e32 v8, v197
	v_mov_b32_e32 v9, v197
	v_mov_b32_e32 v10, v197
	v_mov_b32_e32 v11, v197
	v_mov_b32_e32 v12, v197
	v_mov_b32_e32 v13, v197
	v_mov_b64_e32 v[62:63], v[14:15]
	v_mov_b64_e32 v[46:47], v[14:15]
	v_mov_b64_e32 v[30:31], v[14:15]
	v_add_u32_e32 v186, v185, v196
	v_mov_b64_e32 v[60:61], v[12:13]
	v_mov_b64_e32 v[58:59], v[10:11]
	v_mov_b64_e32 v[56:57], v[8:9]
	v_mov_b64_e32 v[54:55], v[6:7]
	v_mov_b64_e32 v[52:53], v[4:5]
	v_mov_b64_e32 v[50:51], v[2:3]
	v_mov_b64_e32 v[48:49], v[0:1]
	v_mov_b64_e32 v[44:45], v[12:13]
	v_mov_b64_e32 v[42:43], v[10:11]
	v_mov_b64_e32 v[40:41], v[8:9]
	v_mov_b64_e32 v[38:39], v[6:7]
	v_mov_b64_e32 v[36:37], v[4:5]
	v_mov_b64_e32 v[34:35], v[2:3]
	v_mov_b64_e32 v[32:33], v[0:1]
	v_mov_b64_e32 v[28:29], v[12:13]
	v_mov_b64_e32 v[26:27], v[10:11]
	v_mov_b64_e32 v[24:25], v[8:9]
	v_mov_b64_e32 v[22:23], v[6:7]
	v_mov_b64_e32 v[20:21], v[4:5]
	v_mov_b64_e32 v[18:19], v[2:3]
	v_mov_b64_e32 v[16:17], v[0:1]
	s_waitcnt lgkmcnt(0)
	s_barrier
; #define SBAR() __builtin_amdgcn_sched_barrier(0)
; #define SLOAD(k0) do { const char* Vt_ = (const char*)(Vh + (size_t)(k0) * ldv); const char* Kt_ = (const char*)(Kh + (size_t)(k0) * ldk); \
;     svs0 = *(const bf16x8*)(Vt_ + voff); svs1 = *(const bf16x8*)(Vt_ + vstep + voff); \
;     _Pragma("unroll") for (int i_ = 0; i_ < NKP; ++i_) sks[i_] = *(const bf16x8*)(Kt_ + koff[i_]); } while (0)
; #define SWAIT() asm volatile("s_waitcnt vmcnt(0)" ::: "memory")
; template <int DQK, int NQR>
; DEV void qkt(f32x16& p0, f32x16& p1, const char* Ks, const bf16x8* qr, const char* qlds_, int r32, int hi) {
;   constexpr int KROW = ACfg<DQK>::KROW;
;   unsigned qa = (unsigned)(uintptr_t)qlds_; asm volatile("" : "+v"(qa));
;   const __attribute__((address_space(3))) char* qlds = (const __attribute__((address_space(3))) char*)qa;
; #pragma unroll
;   for (int r = 0; r < 16; ++r) { p0[r] = 0.f; p1[r] = 0.f; }
; #pragma unroll
;   for (int d0 = 0; d0 < DQK / 16; ++d0) {
;     const int cb = (d0 * 16 + hi * 8) * 2;
;     bf16x8 b0 = *reinterpret_cast<const bf16x8*>(Ks + r32 * KROW + cb);
;     bf16x8 b1 = *reinterpret_cast<const bf16x8*>(Ks + (32 + r32) * KROW + cb);
;     bf16x8 q;
;     if (d0 < NQR) q = qr[d0 < NQR ? d0 : 0]; else q = *reinterpret_cast<const __attribute__((address_space(3))) bf16x8*>(qlds + (d0 - NQR) * 1024);
;     p0 = __builtin_amdgcn_mfma_f32_32x32x16_bf16(b0, q, p0, 0, 0, 0);
;     p1 = __builtin_amdgcn_mfma_f32_32x32x16_bf16(b1, q, p1, 0, 0, 0);
;     if (NQR < DQK / 16 && (d0 & 3) == 3) SBAR();
;   }
; }
; template <int DQK, bool WIN, bool TWO>
; DEV void attn_unit(const bf16_t* Qb, int ldq, const bf16_t* __restrict__ Kh, int ldk, const bf16_t* __restrict__ Vh, int ldv,
;                    bf16_t* Ob, int ldo, int kbeg, int NT, int q0, float sink, const float SCALE, char* lds) {
;     ...
;   for (int j = 0; j < NT; ++j) {
;     const int bf = j & 1;
;     if (j + 1 < NT) SLOAD(kbeg + (j + 1) * 64);
;     SBAR(); qkt<DQK, NQR>(pA0, pA1, K_lds + bf * KT, qr, qlds, r32, hi);
;     partialSM<WIN>(pA0, pA1, m_reg, mnA, alA, C, thr_raw, KDIFF(j));
;     RESC(alA);
;     finishSM(pA0, pA1, alA, l_reg, pa0, pa1, pa2, pa3); SBAR();
;     if (j + 1 < NT) { SWAIT(); if (bf) SWRITE(0); else SWRITE(1); }
.LBB0_461:
	s_setprio 2
	s_and_b32 s18, s24, 1
	s_mul_i32 s2, s18, 0x6400
	v_add_u32_e32 v202, s2, v186
	ds_read_b128 v[188:191], v202 offset:32768
	ds_read_b128 v[198:201], v202 offset:45568
	ds_read_b128 v[214:217], v202 offset:32800
	ds_read_b128 v[218:221], v202 offset:45600
	ds_read_b128 v[222:225], v202 offset:32832
	ds_read_b128 v[242:245], v202 offset:45632
	global_load_dwordx4 v[144:147], v[246:247], off
	global_load_dwordx4 v[148:151], v[170:171], off
	global_load_dwordx4 v[152:155], v[164:165], off
	global_load_dwordx4 v[156:159], v[166:167], off
	global_load_dwordx4 v[160:163], v[168:169], off
	s_waitcnt lgkmcnt(4)
	v_mfma_f32_32x32x16_bf16 v[80:95], v[188:191], v[140:143], v[226:241]
	v_mfma_f32_32x32x16_bf16 v[64:79], v[198:201], v[140:143], v[226:241]
	ds_read_b128 v[188:191], v202 offset:32864
	ds_read_b128 v[198:201], v202 offset:45664
	s_waitcnt lgkmcnt(4)
	v_mfma_f32_32x32x16_bf16 v[80:95], v[214:217], v[136:139], v[80:95]
	v_mfma_f32_32x32x16_bf16 v[64:79], v[218:221], v[136:139], v[64:79]
	ds_read_b128 v[214:217], v202 offset:32896
	ds_read_b128 v[218:221], v202 offset:45696
	s_waitcnt lgkmcnt(4)
	v_mfma_f32_32x32x16_bf16 v[80:95], v[222:225], v[132:135], v[80:95]
	v_mfma_f32_32x32x16_bf16 v[64:79], v[242:245], v[132:135], v[64:79]
	ds_read_b128 v[222:225], v202 offset:32928
	ds_read_b128 v[242:245], v202 offset:45728
	s_waitcnt lgkmcnt(4)
	v_mfma_f32_32x32x16_bf16 v[80:95], v[188:191], v[128:131], v[80:95]
	v_mfma_f32_32x32x16_bf16 v[64:79], v[198:201], v[128:131], v[64:79]
	ds_read_b128 v[188:191], v202 offset:32960
	ds_read_b128 v[198:201], v202 offset:45760
	s_waitcnt lgkmcnt(4)
	v_mfma_f32_32x32x16_bf16 v[80:95], v[214:217], v[124:127], v[80:95]
	v_mfma_f32_32x32x16_bf16 v[64:79], v[218:221], v[124:127], v[64:79]
	ds_read_b128 v[214:217], v202 offset:32992
	ds_read_b128 v[218:221], v202 offset:45792
	s_waitcnt lgkmcnt(4)
	v_mfma_f32_32x32x16_bf16 v[80:95], v[222:225], v[120:123], v[80:95]
	v_mfma_f32_32x32x16_bf16 v[64:79], v[242:245], v[120:123], v[64:79]
	ds_read_b128 v[222:225], v202 offset:33024
	ds_read_b128 v[242:245], v202 offset:45824
	s_waitcnt lgkmcnt(4)
	v_mfma_f32_32x32x16_bf16 v[80:95], v[188:191], v[116:119], v[80:95]
	v_mfma_f32_32x32x16_bf16 v[64:79], v[198:201], v[116:119], v[64:79]
	ds_read_b128 v[188:191], v202 offset:33056
	ds_read_b128 v[198:201], v202 offset:45856
	s_waitcnt lgkmcnt(4)
	v_mfma_f32_32x32x16_bf16 v[80:95], v[214:217], v[112:115], v[80:95]
	v_mfma_f32_32x32x16_bf16 v[64:79], v[218:221], v[112:115], v[64:79]
	ds_read_b128 v[214:217], v202 offset:33088
	ds_read_b128 v[218:221], v202 offset:45888
	s_waitcnt lgkmcnt(4)
	v_mfma_f32_32x32x16_bf16 v[80:95], v[222:225], v[108:111], v[80:95]
	v_mfma_f32_32x32x16_bf16 v[64:79], v[242:245], v[108:111], v[64:79]
	ds_read_b128 v[222:225], v202 offset:33120
	ds_read_b128 v[242:245], v202 offset:45920
	s_bitcmp0_b32 s100, 0
	s_cbranch_scc1 .Lmla_qk_lead
	s_waitcnt vmcnt(0)
	s_add_i32 s3, s101, 1
	s_cmp_eq_u32 s3, 3
	s_cselect_b32 s3, 0, s3
	s_lshl_b32 s2, s3, 14
	s_cmp_eq_u32 s3, 2
	s_cselect_b32 s3, 0x15000, s2
	s_xor_b32 s2, s18, 1
	s_mul_i32 s2, s2, 0x6400
	v_add_u32_e32 v202, s3, v179
	v_add_u32_e32 v203, s3, v180
	v_add_u32_e32 v213, s2, v182
	ds_write_b128 v202, v[144:147]
	ds_write_b128 v203, v[148:151]
	ds_write_b128 v213, v[152:155] offset:32768
	v_add_u32_e32 v202, s2, v183
	v_add_u32_e32 v203, s2, v184
	ds_write_b128 v202, v[156:159] offset:32768
	ds_write_b128 v203, v[160:163] offset:32768
	s_waitcnt lgkmcnt(9)
	v_mfma_f32_32x32x16_bf16 v[80:95], v[188:191], v[104:107], v[80:95]
	v_mfma_f32_32x32x16_bf16 v[64:79], v[198:201], v[104:107], v[64:79]
	s_waitcnt lgkmcnt(7)
	v_mfma_f32_32x32x16_bf16 v[80:95], v[214:217], v[100:103], v[80:95]
	v_mfma_f32_32x32x16_bf16 v[64:79], v[218:221], v[100:103], v[64:79]
	s_waitcnt lgkmcnt(5)
	v_mfma_f32_32x32x16_bf16 v[80:95], v[222:225], v[96:99], v[80:95]
	v_mfma_f32_32x32x16_bf16 v[64:79], v[242:245], v[96:99], v[64:79]
	s_setprio 0
	s_waitcnt lgkmcnt(0)
	s_barrier
	s_nop 7
	s_nop 0
	s_branch .Lmla_lead_mid
.Lmla_qk_lead:
	s_waitcnt lgkmcnt(4)
	v_mfma_f32_32x32x16_bf16 v[80:95], v[188:191], v[104:107], v[80:95]
	v_mfma_f32_32x32x16_bf16 v[64:79], v[198:201], v[104:107], v[64:79]
	s_waitcnt lgkmcnt(2)
	v_mfma_f32_32x32x16_bf16 v[80:95], v[214:217], v[100:103], v[80:95]
	v_mfma_f32_32x32x16_bf16 v[64:79], v[218:221], v[100:103], v[64:79]
	s_waitcnt lgkmcnt(0)
	v_mfma_f32_32x32x16_bf16 v[80:95], v[222:225], v[96:99], v[80:95]
	v_mfma_f32_32x32x16_bf16 v[64:79], v[242:245], v[96:99], v[64:79]
	s_setprio 0
	s_waitcnt vmcnt(0)
	s_add_i32 s3, s101, 1
	s_cmp_eq_u32 s3, 3
	s_cselect_b32 s3, 0, s3
	s_lshl_b32 s2, s3, 14
	s_cmp_eq_u32 s3, 2
	s_cselect_b32 s3, 0x15000, s2
	s_xor_b32 s2, s18, 1
	s_mul_i32 s2, s2, 0x6400
	v_add_u32_e32 v198, s3, v179
	v_add_u32_e32 v199, s3, v180
	v_add_u32_e32 v200, s2, v182
	v_add_u32_e32 v201, s2, v183
	v_add_u32_e32 v202, s2, v184
	ds_write_b128 v198, v[144:147]
	ds_write_b128 v199, v[148:151]
	ds_write_b128 v200, v[152:155] offset:32768
	ds_write_b128 v201, v[156:159] offset:32768
	ds_write_b128 v202, v[160:163] offset:32768

; #define SBAR() __builtin_amdgcn_sched_barrier(0)
; template <int OFF> DEV s16x4 tr_read(int vb) { s16x4 r; asm volatile("ds_read_b64_tr_b16 %0, %1 offset:%2" : "=&v"(r) : "v"(vb), "i"(OFF) : "memory"); return r; }
; template <int D0, bool SPLIT = true> DEV void pv_one(f32x16& od, int vb, bf16x8 pa0, bf16x8 pa1, bf16x8 pa2, bf16x8 pa3) {
;     ...
;   } else {
;     const s16x4 l0 = tr_read<v_rd_off(D0, 0, 0)>(vb), h0 = tr_read<v_rd_off(D0, 0, 1)>(vb), l1 = tr_read<v_rd_off(D0, 1, 0)>(vb), h1 = tr_read<v_rd_off(D0, 1, 1)>(vb);
;     const s16x4 l2 = tr_read<v_rd_off(D0, 2, 0)>(vb), h2 = tr_read<v_rd_off(D0, 2, 1)>(vb), l3 = tr_read<v_rd_off(D0, 3, 0)>(vb), h3 = tr_read<v_rd_off(D0, 3, 1)>(vb);
;     asm volatile("s_waitcnt lgkmcnt(0)" ::: "memory"); SBAR();
;     od = __builtin_amdgcn_mfma_f32_32x32x16_bf16(pa0, PK(l0, h0), od, 0, 0, 0);
;     od = __builtin_amdgcn_mfma_f32_32x32x16_bf16(pa1, PK(l1, h1), od, 0, 0, 0);
;     od = __builtin_amdgcn_mfma_f32_32x32x16_bf16(pa2, PK(l2, h2), od, 0, 0, 0);
;     od = __builtin_amdgcn_mfma_f32_32x32x16_bf16(pa3, PK(l3, h3), od, 0, 0, 0);
;   }
;     ...
; }
; template <bool SPLIT = true> DEV void pv_d0(f32x16* o, int vb, bf16x8 pa0, bf16x8 pa1, bf16x8 pa2, bf16x8 pa3) {
;   pv_one<0, SPLIT>(o[0], vb, pa0, pa1, pa2, pa3); pv_one<1, SPLIT>(o[1], vb, pa0, pa1, pa2, pa3); pv_one<2, SPLIT>(o[2], vb, pa0, pa1, pa2, pa3); pv_one<3, SPLIT>(o[3], vb, pa0, pa1, pa2, pa3);
; }
; DEV void finishSM(f32x16& p0, f32x16& p1, float alpha, float& l_reg, bf16x8& pa0, bf16x8& pa1, bf16x8& pa2, bf16x8& pa3) {
;     ...
;   l_reg = l_reg * alpha + ps;
.Lmla_ok:
	s_bitset0_b32 s100, 2
	v_fmac_f32_e32 v144, v187, v188
	s_add_i32 s24, s24, 1
	s_lshl_b32 s2, s101, 14
	s_cmp_eq_u32 s101, 2
	s_cselect_b32 s2, 0x15000, s2
	v_add_u32_e32 v145, s2, v177
	s_setprio 2
	ds_read_b64_tr_b16 v[80:81], v145 offset:0
	ds_read_b64_tr_b16 v[82:83], v145 offset:0x800
	ds_read_b64_tr_b16 v[84:85], v145 offset:0x1000
	ds_read_b64_tr_b16 v[86:87], v145 offset:0x1800
	ds_read_b64_tr_b16 v[88:89], v145 offset:0x2000
	ds_read_b64_tr_b16 v[90:91], v145 offset:0x2800
	ds_read_b64_tr_b16 v[92:93], v145 offset:0x3000
	ds_read_b64_tr_b16 v[94:95], v145 offset:0x3800
	s_waitcnt lgkmcnt(0)
	s_nop 0
	v_mfma_f32_32x32x16_bf16 v[0:15], v[68:71], v[80:83], v[0:15]
	ds_read_b64_tr_b16 v[80:81], v145 offset:0x200
	ds_read_b64_tr_b16 v[82:83], v145 offset:0xa00
	v_mfma_f32_32x32x16_bf16 v[0:15], v[72:75], v[84:87], v[0:15]
	ds_read_b64_tr_b16 v[84:85], v145 offset:0x1200
	ds_read_b64_tr_b16 v[86:87], v145 offset:0x1a00
	v_mfma_f32_32x32x16_bf16 v[0:15], v[76:79], v[88:91], v[0:15]
	ds_read_b64_tr_b16 v[88:89], v145 offset:0x2200
	ds_read_b64_tr_b16 v[90:91], v145 offset:0x2a00
	v_mfma_f32_32x32x16_bf16 v[0:15], v[64:67], v[92:95], v[0:15]
	ds_read_b64_tr_b16 v[92:93], v145 offset:0x3200
	ds_read_b64_tr_b16 v[94:95], v145 offset:0x3a00
	s_waitcnt lgkmcnt(0)
	v_mfma_f32_32x32x16_bf16 v[48:63], v[68:71], v[80:83], v[48:63]
	ds_read_b64_tr_b16 v[80:81], v145 offset:0x400
	ds_read_b64_tr_b16 v[82:83], v145 offset:0xc00
	v_mfma_f32_32x32x16_bf16 v[48:63], v[72:75], v[84:87], v[48:63]
	ds_read_b64_tr_b16 v[84:85], v145 offset:0x1400
	ds_read_b64_tr_b16 v[86:87], v145 offset:0x1c00
	v_mfma_f32_32x32x16_bf16 v[48:63], v[76:79], v[88:91], v[48:63]
	ds_read_b64_tr_b16 v[88:89], v145 offset:0x2400
	ds_read_b64_tr_b16 v[90:91], v145 offset:0x2c00
	v_mfma_f32_32x32x16_bf16 v[48:63], v[64:67], v[92:95], v[48:63]
	ds_read_b64_tr_b16 v[92:93], v145 offset:0x3400
	ds_read_b64_tr_b16 v[94:95], v145 offset:0x3c00
	s_waitcnt lgkmcnt(0)
	v_mfma_f32_32x32x16_bf16 v[32:47], v[68:71], v[80:83], v[32:47]
	ds_read_b64_tr_b16 v[80:81], v145 offset:0x600
	ds_read_b64_tr_b16 v[82:83], v145 offset:0xe00
	v_mfma_f32_32x32x16_bf16 v[32:47], v[72:75], v[84:87], v[32:47]
	ds_read_b64_tr_b16 v[84:85], v145 offset:0x1600
	ds_read_b64_tr_b16 v[86:87], v145 offset:0x1e00
	v_mfma_f32_32x32x16_bf16 v[32:47], v[76:79], v[88:91], v[32:47]
	ds_read_b64_tr_b16 v[88:89], v145 offset:0x2600
	ds_read_b64_tr_b16 v[90:91], v145 offset:0x2e00
	v_mfma_f32_32x32x16_bf16 v[32:47], v[64:67], v[92:95], v[32:47]
	ds_read_b64_tr_b16 v[92:93], v145 offset:0x3600
	ds_read_b64_tr_b16 v[94:95], v145 offset:0x3e00
	s_waitcnt lgkmcnt(0)
	v_mfma_f32_32x32x16_bf16 v[16:31], v[68:71], v[80:83], v[16:31]
	s_mov_b64 s[2:3], 0x20000
	v_lshl_add_u64 v[164:165], v[164:165], 0, s[62:63]
	v_lshl_add_u64 v[166:167], v[166:167], 0, s[62:63]
	v_lshl_add_u64 v[168:169], v[168:169], 0, s[62:63]
	v_lshl_add_u64 v[170:171], v[170:171], 0, s[2:3]
	v_lshl_add_u64 v[246:247], v[246:247], 0, s[2:3]
	s_add_i32 s101, s101, 1
	s_cmp_eq_u32 s101, 3
	s_cselect_b32 s101, 0, s101
	s_waitcnt lgkmcnt(0)
	s_bitcmp1_b32 s100, 0
	s_cbranch_scc1 .Lmla_trail_end
	s_barrier
.Lmla_trail_end:
	v_mfma_f32_32x32x16_bf16 v[16:31], v[72:75], v[84:87], v[16:31]
	v_mfma_f32_32x32x16_bf16 v[16:31], v[76:79], v[88:91], v[16:31]
	v_mfma_f32_32x32x16_bf16 v[16:31], v[64:67], v[92:95], v[16:31]
	s_setprio 0
	s_cmp_eq_u32 s20, s24
	s_cbranch_scc1 .LBB0_471
	v_mov_b32_e32 v187, v144
	s_branch .LBB0_461
